# widened G4 epilogue stores, and that epilogue's flat loads/stores as global
# speedup vs baseline: 1.0040x; 1.0040x over previous
; #define ROPE_FETCH(ai_, m_) do { const int s_ = (u.pm * BM + (ai_) * HALF + wr * 64 + (m_) * 16 + fr) & 2047, pos_ = (wc & 1) ? (s_ & 63) : (s_ >> 6); \
;             n01 = *(const f32x4*)(rope + pos_ * 16 + 4 * fq); n23 = *(const f32x4*)(rope + pos_ * 16 + 4 * fq + 2); } while (0)
;     __device__ __forceinline__ void operator()(const f32x4 (&acc)[2][2][4][2], const Unit& u, int wr, int wc, int fr, int fq) const {
;     ...
;         if (do_rope) ROPE_FETCH(0, 0);
; #pragma unroll
;         for (int ai = 0; ai < 2; ++ai)
; #pragma unroll
;             for (int m = 0; m < 4; ++m) {
;                 const f32x4 c01 = n01, c23 = n23;
;                 if (do_rope && (ai * 4 + m) < 7) ROPE_FETCH((ai * 4 + m + 1) >> 2, (ai * 4 + m + 1) & 3);
.LBB0_199:
	v_mov_b64_e32 v[144:145], v[140:141]
	s_andn2_b64 vcc, exec, s[22:23]
	v_mov_b64_e32 v[142:143], v[138:139]
	s_cbranch_vccnz .LBB0_201
	s_lshl_b32 s14, s3, 2
	s_add_i32 s14, s14, s67
	s_and_b32 s14, s14, 31
	v_mov_b32_e32 v0, s14
	v_cndmask_b32_e64 v0, v151, v0, s[38:39]
	v_lshlrev_b32_e32 v0, 7, v0
	v_lshl_add_u64 v[122:123], v[152:153], 0, v[0:1]
	global_load_dwordx4 v[142:145], v[122:123], off
	global_load_dwordx4 v[138:141], v[122:123], off offset:16
.LBB0_201:
	v_cndmask_b32_e64 v0, 0, 1, s[18:19]
	s_waitcnt vmcnt(0) lgkmcnt(0)
	v_mov_b64_e32 v[126:127], v[138:139]
	v_mov_b64_e32 v[122:123], v[142:143]
	s_lshl_b32 s29, s3, 8
	v_cmp_ne_u32_e64 s[54:55], 1, v0
	s_andn2_b64 vcc, exec, s[18:19]
	v_mov_b64_e32 v[128:129], v[140:141]
	v_mov_b64_e32 v[124:125], v[144:145]
	s_cbranch_vccnz .LBB0_203
	s_lshr_b32 s3, s29, 6
	s_add_i32 s3, s3, s67
	s_and_b32 s3, s3, 31
	v_mov_b32_e32 v0, s3
	v_cndmask_b32_e64 v0, v208, v0, s[38:39]
	v_lshlrev_b32_e32 v0, 7, v0
	v_lshl_add_u64 v[126:127], v[152:153], 0, v[0:1]
	global_load_dwordx4 v[122:125], v[126:127], off
	s_nop 0
	global_load_dwordx4 v[126:129], v[126:127], off offset:16

;     __device__ __forceinline__ void operator()(const f32x4 (&acc)[2][2][4][2], const Unit& u, int wr, int wc, int fr, int fq) const {
;     ...
;                     f32x4 v0 = acc[ai][bj][m][0], v1 = acc[ai][bj][m][1];
;                     const bool is_rope = (pn >= 2 && pn <= 6) || (pn == 9 && bj == 0);
;                     if (is_rope && lat) {
;                         const float cs[4] = {c01[0], c01[2], c23[0], c23[2]}, sn[4] = {c01[1], c01[3], c23[1], c23[3]};
; #pragma unroll
;                         for (int i = 0; i < 4; ++i) { const float x0 = v0[i], x1 = v1[i]; v0[i] = x0 * cs[i] - x1 * sn[i]; v1[i] = x1 * cs[i] + x0 * sn[i]; }
;                     }
.LBB0_221:
	s_and_b64 s[18:19], s[44:45], s[18:19]
	v_cndmask_b32_e64 v130, 0, 1, s[18:19]
	v_cmp_ne_u32_e64 s[50:51], 1, v130
	s_andn2_b64 vcc, exec, s[18:19]
	v_mov_b64_e32 v[218:219], v[182:183]
	s_nop 1
	v_permlane16_swap_b32_e32 v216, v218
	v_permlane16_swap_b32_e32 v217, v219
	v_lshl_add_u64 v[220:221], v[180:181], 0, v[222:223]
	global_store_dwordx4 v[220:221], v[216:219], off
	s_cbranch_vccnz .LBB0_223
	v_mul_f32_e32 v134, v120, v138
	v_mul_f32_e32 v136, v116, v139
	v_mul_f32_e32 v138, v116, v138
	v_mov_b32_e32 v116, v121
	v_mov_b32_e32 v130, v142
	v_mov_b32_e32 v131, v144
	v_mov_b32_e32 v144, v143
	v_mul_f32_e32 v142, v120, v139
	v_pk_mul_f32 v[180:181], v[116:117], v[140:141]
	v_mov_b32_e32 v120, v117
	v_pk_mul_f32 v[132:133], v[114:115], v[144:145]
	v_mov_b32_e32 v135, v180
	v_mov_b32_e32 v137, v181
	v_pk_mul_f32 v[116:117], v[120:121], v[140:141]
	v_pk_mul_f32 v[114:115], v[114:115], v[130:131]
	v_pk_fma_f32 v[130:131], v[118:119], v[130:131], v[132:133] neg_lo:[0,0,1] neg_hi:[0,0,1]
	v_pk_add_f32 v[132:133], v[134:135], v[136:137] neg_lo:[0,1] neg_hi:[0,1]
	v_mov_b32_e32 v143, v117
	v_mov_b32_e32 v139, v116
	v_pk_fma_f32 v[114:115], v[118:119], v[144:145], v[114:115]
	v_pk_add_f32 v[116:117], v[142:143], v[138:139]
	v_mov_b32_e32 v118, v130
	v_mov_b32_e32 v119, v131
	v_mov_b32_e32 v120, v132
	v_mov_b32_e32 v121, v133

; #define ROPE_FETCH(ai_, m_) do { const int s_ = (u.pm * BM + (ai_) * HALF + wr * 64 + (m_) * 16 + fr) & 2047, pos_ = (wc & 1) ? (s_ & 63) : (s_ >> 6); \
;             n01 = *(const f32x4*)(rope + pos_ * 16 + 4 * fq); n23 = *(const f32x4*)(rope + pos_ * 16 + 4 * fq + 2); } while (0)
;     __device__ __forceinline__ void operator()(const f32x4 (&acc)[2][2][4][2], const Unit& u, int wr, int wc, int fr, int fq) const {
;     ...
;         if (do_rope) ROPE_FETCH(0, 0);
; #pragma unroll
;         for (int ai = 0; ai < 2; ++ai)
; #pragma unroll
;             for (int m = 0; m < 4; ++m) {
;                 const f32x4 c01 = n01, c23 = n23;
;                 if (do_rope && (ai * 4 + m) < 7) ROPE_FETCH((ai * 4 + m + 1) >> 2, (ai * 4 + m + 1) & 3);
.LBB0_239:
	v_mov_b64_e32 v[218:219], v[132:133]
	s_nop 1
	v_permlane16_swap_b32_e32 v216, v218
	v_permlane16_swap_b32_e32 v217, v219
	v_lshl_add_u64 v[220:221], v[130:131], 0, v[222:223]
	global_store_dwordx4 v[220:221], v[216:219], off
	s_waitcnt vmcnt(0) lgkmcnt(0)
	v_mov_b64_e32 v[118:119], v[126:127]
	v_mov_b64_e32 v[114:115], v[122:123]
	s_and_b64 vcc, exec, s[54:55]
	v_mov_b64_e32 v[120:121], v[128:129]
	v_mov_b64_e32 v[116:117], v[124:125]
	s_cbranch_vccnz .LBB0_241
	s_lshr_b32 s15, s29, 6
	s_add_i32 s15, s15, s67
	s_and_b32 s15, s15, 31
	v_mov_b32_e32 v0, s15
	v_cndmask_b32_e64 v0, v209, v0, s[38:39]
	v_lshlrev_b32_e32 v0, 7, v0
	v_lshl_add_u64 v[118:119], v[152:153], 0, v[0:1]
	global_load_dwordx4 v[114:117], v[118:119], off
	s_nop 0
	global_load_dwordx4 v[118:121], v[118:119], off offset:16

;     __device__ __forceinline__ void operator()(const f32x4 (&acc)[2][2][4][2], const Unit& u, int wr, int wc, int fr, int fq) const {
;     ...
;                     if (pn <= 1) {
; #pragma unroll
;                         for (int i = 0; i < 4; ++i) { v0[i] = gelu_tanh_f(v0[i]); v1[i] = gelu_tanh_f(v1[i]); }
;                         bf16_t* p = UV + (size_t)r * 512 + pn * 256 + ctb;
;                         *(u32x2*)p = (u32x2){cvt_pk_bf16(v0[0], v0[1]), cvt_pk_bf16(v0[2], v0[3])}; *(u32x2*)(p + 16) = (u32x2){cvt_pk_bf16(v1[0], v1[1]), cvt_pk_bf16(v1[2], v1[3])};
;                     } else if (pn <= 4) {
;                         v0 = v0 * QSCALE; v1 = v1 * QSCALE;
;                         bf16_t* p = (pn <= 3) ? QB + (size_t)r * 512 + (pn - 2) * 256 + ctb : QC + (size_t)r * 256 + ctb;
;                         *(u32x2*)p = (u32x2){cvt_pk_bf16(v0[0], v0[1]), cvt_pk_bf16(v0[2], v0[3])}; *(u32x2*)(p + 16) = (u32x2){cvt_pk_bf16(v1[0], v1[1]), cvt_pk_bf16(v1[2], v1[3])};
;                     } else if (pn <= 6) {
;                         const int ck = (pn - 5) * 256 + ctb, head = ck >> 7, cw = ck & 127;
;                         bf16_t* p = KB + ((size_t)(b * 4 + head) * NKEY + keyidx) * 128 + cw;
;                         *(u32x2*)p = (u32x2){cvt_pk_bf16(v0[0], v0[1]), cvt_pk_bf16(v0[2], v0[3])}; *(u32x2*)(p + 16) = (u32x2){cvt_pk_bf16(v1[0], v1[1]), cvt_pk_bf16(v1[2], v1[3])};
;                     } else if (pn <= 8) {
;                         const int cv = (pn - 7) * 256 + ctb, head = cv >> 7, e = cv & 127;
;                         bf16_t* p = VBt + ((size_t)(b * 4 + head) * NKEY + keyidx) * 128 + e;
;                         *(u32x2*)p = (u32x2){cvt_pk_bf16(v0[0], v0[1]), cvt_pk_bf16(v0[2], v0[3])}; *(u32x2*)(p + 16) = (u32x2){cvt_pk_bf16(v1[0], v1[1]), cvt_pk_bf16(v1[2], v1[3])};
;                     } else {
;                         const int kv = wc >> 1, d = (wc & 1) * 32 + 4 * fq;
;                         if (bj == 0) {
;                             bf16_t* p = KC + ((size_t)(b * 2 + kv) * NKEY + keyidx) * 64 + d;
;                             *(u32x2*)p = (u32x2){cvt_pk_bf16(v0[0], v0[1]), cvt_pk_bf16(v0[2], v0[3])}; *(u32x2*)(p + 16) = (u32x2){cvt_pk_bf16(v1[0], v1[1]), cvt_pk_bf16(v1[2], v1[3])};
;                         } else {
;                             bf16_t* p = VCt + ((size_t)(b * 2 + kv) * NKEY + keyidx) * 64 + d;
.LBB0_257:
	s_and_b64 vcc, exec, s[50:51]
	v_mov_b64_e32 v[218:219], v[140:141]
	s_nop 1
	v_permlane16_swap_b32_e32 v216, v218
	v_permlane16_swap_b32_e32 v217, v219
	v_lshl_add_u64 v[220:221], v[138:139], 0, v[222:223]
	global_store_dwordx4 v[220:221], v[216:219], off
	s_cbranch_vccnz .LBB0_259

; __device__ __forceinline__ unsigned cvt_pk_bf16(float lo, float hi) { unsigned r; asm volatile("v_cvt_pk_bf16_f32 %0, %1, %2" : "=v"(r) : "v"(lo), "v"(hi)); return r; }
; __device__ __forceinline__ float gelu_tanh_f(float x) { const float y = 1.5957691216057308f * (x + 0.044715f * x * x * x); return x * __builtin_amdgcn_rcpf(1.f + __expf(-y)); }
;     __device__ __forceinline__ void operator()(const f32x4 (&acc)[2][2][4][2], const Unit& u, int wr, int wc, int fr, int fq) const {
;     ...
;                     if (pn <= 1) {
; #pragma unroll
;                         for (int i = 0; i < 4; ++i) { v0[i] = gelu_tanh_f(v0[i]); v1[i] = gelu_tanh_f(v1[i]); }
;                         bf16_t* p = UV + (size_t)r * 512 + pn * 256 + ctb;
;                         *(u32x2*)p = (u32x2){cvt_pk_bf16(v0[0], v0[1]), cvt_pk_bf16(v0[2], v0[3])}; *(u32x2*)(p + 16) = (u32x2){cvt_pk_bf16(v1[0], v1[1]), cvt_pk_bf16(v1[2], v1[3])};
.LBB0_274:
	v_mul_f32_e32 v138, 0x3d372713, v110
	v_mul_f32_e32 v138, v110, v138
	v_fma_f32 v138, v110, v138, v110
	v_mul_f32_e32 v138, 0xbfcc422a, v138
	v_mul_f32_e32 v138, 0x3fb8aa3b, v138
	v_exp_f32_e32 v138, v138
	v_mov_b32_e32 v169, v1
	v_add_f32_e32 v138, 1.0, v138
	v_rcp_f32_e32 v138, v138
	s_nop 0
	v_mul_f32_e32 v110, v110, v138
	v_mul_f32_e32 v138, 0x3d372713, v106
	v_mul_f32_e32 v138, v106, v138
	v_fma_f32 v138, v106, v138, v106
	v_mul_f32_e32 v138, 0xbfcc422a, v138
	v_mul_f32_e32 v138, 0x3fb8aa3b, v138
	v_exp_f32_e32 v138, v138
	s_nop 0
	v_add_f32_e32 v138, 1.0, v138
	v_rcp_f32_e32 v138, v138
	s_nop 0
	v_mul_f32_e32 v140, v106, v138
	v_mul_f32_e32 v106, 0x3d372713, v111
	v_mul_f32_e32 v106, v111, v106
	v_fma_f32 v106, v111, v106, v111
	v_mul_f32_e32 v106, 0xbfcc422a, v106
	v_mul_f32_e32 v106, 0x3fb8aa3b, v106
	v_exp_f32_e32 v106, v106
	v_lshl_add_u64 v[138:139], v[130:131], 0, v[168:169]
	v_add_f32_e32 v106, 1.0, v106
	v_rcp_f32_e32 v106, v106
	s_nop 0
	v_mul_f32_e32 v106, v111, v106
	v_mul_f32_e32 v111, 0x3d372713, v107
	v_mul_f32_e32 v111, v107, v111
	v_fma_f32 v111, v107, v111, v107
	v_mul_f32_e32 v111, 0xbfcc422a, v111
	v_mul_f32_e32 v111, 0x3fb8aa3b, v111
	v_exp_f32_e32 v111, v111
	v_cvt_pk_bf16_f32 v106, v110, v106
	s_nop 0
	v_add_f32_e32 v111, 1.0, v111
	v_rcp_f32_e32 v111, v111
	s_nop 0
	v_mul_f32_e32 v111, v107, v111
	v_mul_f32_e32 v107, 0x3d372713, v112
	v_mul_f32_e32 v107, v112, v107
	v_fma_f32 v107, v112, v107, v112
	v_mul_f32_e32 v107, 0xbfcc422a, v107
	v_mul_f32_e32 v107, 0x3fb8aa3b, v107
	v_exp_f32_e32 v107, v107
	s_nop 0
	v_add_f32_e32 v107, 1.0, v107
	v_rcp_f32_e32 v107, v107
	s_nop 0
	v_mul_f32_e32 v107, v112, v107
	v_mul_f32_e32 v112, 0x3d372713, v108
	v_mul_f32_e32 v112, v108, v112
	v_fma_f32 v112, v108, v112, v108
	v_mul_f32_e32 v112, 0xbfcc422a, v112
	v_mul_f32_e32 v112, 0x3fb8aa3b, v112
	v_exp_f32_e32 v112, v112
	s_nop 0
	v_add_f32_e32 v112, 1.0, v112
	v_rcp_f32_e32 v112, v112
	s_nop 0
	v_mul_f32_e32 v108, v108, v112
	v_mul_f32_e32 v112, 0x3d372713, v113
	v_mul_f32_e32 v112, v113, v112
	v_fma_f32 v112, v113, v112, v113
	v_mul_f32_e32 v112, 0xbfcc422a, v112
	v_mul_f32_e32 v112, 0x3fb8aa3b, v112
	v_exp_f32_e32 v112, v112
	s_nop 0
	v_add_f32_e32 v112, 1.0, v112
	v_rcp_f32_e32 v112, v112
	s_nop 0
	v_mul_f32_e32 v112, v113, v112
	v_mul_f32_e32 v113, 0x3d372713, v109
	v_mul_f32_e32 v113, v109, v113
	v_fma_f32 v113, v109, v113, v109
	v_mul_f32_e32 v113, 0xbfcc422a, v113
	v_mul_f32_e32 v113, 0x3fb8aa3b, v113
	v_exp_f32_e32 v113, v113
	v_cvt_pk_bf16_f32 v107, v107, v112
	v_mov_b64_e32 v[216:217], v[106:107]
	v_cvt_pk_bf16_f32 v140, v140, v111
	v_add_f32_e32 v113, 1.0, v113
	v_rcp_f32_e32 v113, v113
	s_nop 0
	v_mul_f32_e32 v109, v109, v113
	v_cvt_pk_bf16_f32 v141, v108, v109
	s_and_b64 vcc, exec, s[50:51]
	v_mov_b64_e32 v[218:219], v[140:141]
	s_nop 1
	v_permlane16_swap_b32_e32 v216, v218
	v_permlane16_swap_b32_e32 v217, v219
	v_lshl_add_u64 v[220:221], v[138:139], 0, v[222:223]
	global_store_dwordx4 v[220:221], v[216:219], off
	s_cbranch_vccnz .LBB0_259
	s_branch .LBB0_258

; #define ROPE_FETCH(ai_, m_) do { const int s_ = (u.pm * BM + (ai_) * HALF + wr * 64 + (m_) * 16 + fr) & 2047, pos_ = (wc & 1) ? (s_ & 63) : (s_ >> 6); \
;             n01 = *(const f32x4*)(rope + pos_ * 16 + 4 * fq); n23 = *(const f32x4*)(rope + pos_ * 16 + 4 * fq + 2); } while (0)
;     __device__ __forceinline__ void operator()(const f32x4 (&acc)[2][2][4][2], const Unit& u, int wr, int wc, int fr, int fq) const {
;     ...
;         if (do_rope) ROPE_FETCH(0, 0);
; #pragma unroll
;         for (int ai = 0; ai < 2; ++ai)
; #pragma unroll
;             for (int m = 0; m < 4; ++m) {
;                 const f32x4 c01 = n01, c23 = n23;
;                 if (do_rope && (ai * 4 + m) < 7) ROPE_FETCH((ai * 4 + m + 1) >> 2, (ai * 4 + m + 1) & 3);
.LBB0_277:
	v_mov_b64_e32 v[218:219], v[108:109]
	s_nop 1
	v_permlane16_swap_b32_e32 v216, v218
	v_permlane16_swap_b32_e32 v217, v219
	v_lshl_add_u64 v[220:221], v[106:107], 0, v[222:223]
	global_store_dwordx4 v[220:221], v[216:219], off
	s_waitcnt vmcnt(0) lgkmcnt(0)
	v_mov_b64_e32 v[102:103], v[118:119]
	v_mov_b64_e32 v[98:99], v[114:115]
	s_and_b64 vcc, exec, s[54:55]
	v_mov_b64_e32 v[104:105], v[120:121]
	v_mov_b64_e32 v[100:101], v[116:117]
	s_cbranch_vccnz .LBB0_279
	s_lshr_b32 s15, s29, 6
	s_add_i32 s15, s15, s67
	s_and_b32 s15, s15, 31
	v_mov_b32_e32 v0, s15
	v_cndmask_b32_e64 v0, v210, v0, s[38:39]
	v_lshlrev_b32_e32 v0, 7, v0
	v_lshl_add_u64 v[102:103], v[152:153], 0, v[0:1]
	global_load_dwordx4 v[98:101], v[102:103], off
	s_nop 0
	global_load_dwordx4 v[102:105], v[102:103], off offset:16

;     __device__ __forceinline__ void operator()(const f32x4 (&acc)[2][2][4][2], const Unit& u, int wr, int wc, int fr, int fq) const {
;     ...
;                     if (pn <= 1) {
; #pragma unroll
;                         for (int i = 0; i < 4; ++i) { v0[i] = gelu_tanh_f(v0[i]); v1[i] = gelu_tanh_f(v1[i]); }
;                         bf16_t* p = UV + (size_t)r * 512 + pn * 256 + ctb;
;                         *(u32x2*)p = (u32x2){cvt_pk_bf16(v0[0], v0[1]), cvt_pk_bf16(v0[2], v0[3])}; *(u32x2*)(p + 16) = (u32x2){cvt_pk_bf16(v1[0], v1[1]), cvt_pk_bf16(v1[2], v1[3])};
;                     } else if (pn <= 4) {
;                         v0 = v0 * QSCALE; v1 = v1 * QSCALE;
;                         bf16_t* p = (pn <= 3) ? QB + (size_t)r * 512 + (pn - 2) * 256 + ctb : QC + (size_t)r * 256 + ctb;
;                         *(u32x2*)p = (u32x2){cvt_pk_bf16(v0[0], v0[1]), cvt_pk_bf16(v0[2], v0[3])}; *(u32x2*)(p + 16) = (u32x2){cvt_pk_bf16(v1[0], v1[1]), cvt_pk_bf16(v1[2], v1[3])};
;                     } else if (pn <= 6) {
;                         const int ck = (pn - 5) * 256 + ctb, head = ck >> 7, cw = ck & 127;
;                         bf16_t* p = KB + ((size_t)(b * 4 + head) * NKEY + keyidx) * 128 + cw;
;                         *(u32x2*)p = (u32x2){cvt_pk_bf16(v0[0], v0[1]), cvt_pk_bf16(v0[2], v0[3])}; *(u32x2*)(p + 16) = (u32x2){cvt_pk_bf16(v1[0], v1[1]), cvt_pk_bf16(v1[2], v1[3])};
;                     } else if (pn <= 8) {
;                         const int cv = (pn - 7) * 256 + ctb, head = cv >> 7, e = cv & 127;
;                         bf16_t* p = VBt + ((size_t)(b * 4 + head) * NKEY + keyidx) * 128 + e;
;                         *(u32x2*)p = (u32x2){cvt_pk_bf16(v0[0], v0[1]), cvt_pk_bf16(v0[2], v0[3])}; *(u32x2*)(p + 16) = (u32x2){cvt_pk_bf16(v1[0], v1[1]), cvt_pk_bf16(v1[2], v1[3])};
;                     } else {
;                         const int kv = wc >> 1, d = (wc & 1) * 32 + 4 * fq;
;                         if (bj == 0) {
;                             bf16_t* p = KC + ((size_t)(b * 2 + kv) * NKEY + keyidx) * 64 + d;
;                             *(u32x2*)p = (u32x2){cvt_pk_bf16(v0[0], v0[1]), cvt_pk_bf16(v0[2], v0[3])}; *(u32x2*)(p + 16) = (u32x2){cvt_pk_bf16(v1[0], v1[1]), cvt_pk_bf16(v1[2], v1[3])};
;                         } else {
;                             bf16_t* p = VCt + ((size_t)(b * 2 + kv) * NKEY + keyidx) * 64 + d;
.LBB0_295:
	s_and_b64 vcc, exec, s[50:51]
	v_mov_b64_e32 v[218:219], v[124:125]
	s_nop 1
	v_permlane16_swap_b32_e32 v216, v218
	v_permlane16_swap_b32_e32 v217, v219
	v_lshl_add_u64 v[220:221], v[122:123], 0, v[222:223]
	global_store_dwordx4 v[220:221], v[216:219], off
	s_cbranch_vccnz .LBB0_297

; __device__ __forceinline__ unsigned cvt_pk_bf16(float lo, float hi) { unsigned r; asm volatile("v_cvt_pk_bf16_f32 %0, %1, %2" : "=v"(r) : "v"(lo), "v"(hi)); return r; }
; __device__ __forceinline__ float gelu_tanh_f(float x) { const float y = 1.5957691216057308f * (x + 0.044715f * x * x * x); return x * __builtin_amdgcn_rcpf(1.f + __expf(-y)); }
;     __device__ __forceinline__ void operator()(const f32x4 (&acc)[2][2][4][2], const Unit& u, int wr, int wc, int fr, int fq) const {
;     ...
;                     if (pn <= 1) {
; #pragma unroll
;                         for (int i = 0; i < 4; ++i) { v0[i] = gelu_tanh_f(v0[i]); v1[i] = gelu_tanh_f(v1[i]); }
;                         bf16_t* p = UV + (size_t)r * 512 + pn * 256 + ctb;
;                         *(u32x2*)p = (u32x2){cvt_pk_bf16(v0[0], v0[1]), cvt_pk_bf16(v0[2], v0[3])}; *(u32x2*)(p + 16) = (u32x2){cvt_pk_bf16(v1[0], v1[1]), cvt_pk_bf16(v1[2], v1[3])};
.LBB0_312:
	v_mul_f32_e32 v122, 0x3d372713, v94
	v_mul_f32_e32 v122, v94, v122
	v_fma_f32 v122, v94, v122, v94
	v_mul_f32_e32 v122, 0xbfcc422a, v122
	v_mul_f32_e32 v122, 0x3fb8aa3b, v122
	v_exp_f32_e32 v122, v122
	v_mov_b32_e32 v169, v1
	v_add_f32_e32 v122, 1.0, v122
	v_rcp_f32_e32 v122, v122
	s_nop 0
	v_mul_f32_e32 v94, v94, v122
	v_mul_f32_e32 v122, 0x3d372713, v90
	v_mul_f32_e32 v122, v90, v122
	v_fma_f32 v122, v90, v122, v90
	v_mul_f32_e32 v122, 0xbfcc422a, v122
	v_mul_f32_e32 v122, 0x3fb8aa3b, v122
	v_exp_f32_e32 v122, v122
	s_nop 0
	v_add_f32_e32 v122, 1.0, v122
	v_rcp_f32_e32 v122, v122
	s_nop 0
	v_mul_f32_e32 v124, v90, v122
	v_mul_f32_e32 v90, 0x3d372713, v95
	v_mul_f32_e32 v90, v95, v90
	v_fma_f32 v90, v95, v90, v95
	v_mul_f32_e32 v90, 0xbfcc422a, v90
	v_mul_f32_e32 v90, 0x3fb8aa3b, v90
	v_exp_f32_e32 v90, v90
	v_lshl_add_u64 v[122:123], v[106:107], 0, v[168:169]
	v_add_f32_e32 v90, 1.0, v90
	v_rcp_f32_e32 v90, v90
	s_nop 0
	v_mul_f32_e32 v90, v95, v90
	v_mul_f32_e32 v95, 0x3d372713, v91
	v_mul_f32_e32 v95, v91, v95
	v_fma_f32 v95, v91, v95, v91
	v_mul_f32_e32 v95, 0xbfcc422a, v95
	v_mul_f32_e32 v95, 0x3fb8aa3b, v95
	v_exp_f32_e32 v95, v95
	v_cvt_pk_bf16_f32 v90, v94, v90
	s_nop 0
	v_add_f32_e32 v95, 1.0, v95
	v_rcp_f32_e32 v95, v95
	s_nop 0
	v_mul_f32_e32 v95, v91, v95
	v_mul_f32_e32 v91, 0x3d372713, v96
	v_mul_f32_e32 v91, v96, v91
	v_fma_f32 v91, v96, v91, v96
	v_mul_f32_e32 v91, 0xbfcc422a, v91
	v_mul_f32_e32 v91, 0x3fb8aa3b, v91
	v_exp_f32_e32 v91, v91
	s_nop 0
	v_add_f32_e32 v91, 1.0, v91
	v_rcp_f32_e32 v91, v91
	s_nop 0
	v_mul_f32_e32 v91, v96, v91
	v_mul_f32_e32 v96, 0x3d372713, v92
	v_mul_f32_e32 v96, v92, v96
	v_fma_f32 v96, v92, v96, v92
	v_mul_f32_e32 v96, 0xbfcc422a, v96
	v_mul_f32_e32 v96, 0x3fb8aa3b, v96
	v_exp_f32_e32 v96, v96
	s_nop 0
	v_add_f32_e32 v96, 1.0, v96
	v_rcp_f32_e32 v96, v96
	s_nop 0
	v_mul_f32_e32 v92, v92, v96
	v_mul_f32_e32 v96, 0x3d372713, v97
	v_mul_f32_e32 v96, v97, v96
	v_fma_f32 v96, v97, v96, v97
	v_mul_f32_e32 v96, 0xbfcc422a, v96
	v_mul_f32_e32 v96, 0x3fb8aa3b, v96
	v_exp_f32_e32 v96, v96
	s_nop 0
	v_add_f32_e32 v96, 1.0, v96
	v_rcp_f32_e32 v96, v96
	s_nop 0
	v_mul_f32_e32 v96, v97, v96
	v_mul_f32_e32 v97, 0x3d372713, v93
	v_mul_f32_e32 v97, v93, v97
	v_fma_f32 v97, v93, v97, v93
	v_mul_f32_e32 v97, 0xbfcc422a, v97
	v_mul_f32_e32 v97, 0x3fb8aa3b, v97
	v_exp_f32_e32 v97, v97
	v_cvt_pk_bf16_f32 v91, v91, v96
	v_mov_b64_e32 v[216:217], v[90:91]
	v_cvt_pk_bf16_f32 v124, v124, v95
	v_add_f32_e32 v97, 1.0, v97
	v_rcp_f32_e32 v97, v97
	s_nop 0
	v_mul_f32_e32 v93, v93, v97
	v_cvt_pk_bf16_f32 v125, v92, v93
	s_and_b64 vcc, exec, s[50:51]
	v_mov_b64_e32 v[218:219], v[124:125]
	s_nop 1
	v_permlane16_swap_b32_e32 v216, v218
	v_permlane16_swap_b32_e32 v217, v219
	v_lshl_add_u64 v[220:221], v[122:123], 0, v[222:223]
	global_store_dwordx4 v[220:221], v[216:219], off
	s_cbranch_vccnz .LBB0_297
	s_branch .LBB0_296

; #define ROPE_FETCH(ai_, m_) do { const int s_ = (u.pm * BM + (ai_) * HALF + wr * 64 + (m_) * 16 + fr) & 2047, pos_ = (wc & 1) ? (s_ & 63) : (s_ >> 6); \
;             n01 = *(const f32x4*)(rope + pos_ * 16 + 4 * fq); n23 = *(const f32x4*)(rope + pos_ * 16 + 4 * fq + 2); } while (0)
;     __device__ __forceinline__ void operator()(const f32x4 (&acc)[2][2][4][2], const Unit& u, int wr, int wc, int fr, int fq) const {
;     ...
;         if (do_rope) ROPE_FETCH(0, 0);
; #pragma unroll
;         for (int ai = 0; ai < 2; ++ai)
; #pragma unroll
;             for (int m = 0; m < 4; ++m) {
;                 const f32x4 c01 = n01, c23 = n23;
;                 if (do_rope && (ai * 4 + m) < 7) ROPE_FETCH((ai * 4 + m + 1) >> 2, (ai * 4 + m + 1) & 3);
.LBB0_315:
	v_mov_b64_e32 v[218:219], v[92:93]
	s_nop 1
	v_permlane16_swap_b32_e32 v216, v218
	v_permlane16_swap_b32_e32 v217, v219
	v_lshl_add_u64 v[220:221], v[90:91], 0, v[222:223]
	global_store_dwordx4 v[220:221], v[216:219], off
	s_waitcnt vmcnt(0) lgkmcnt(0)
	v_mov_b64_e32 v[86:87], v[102:103]
	v_mov_b64_e32 v[82:83], v[98:99]
	s_and_b64 vcc, exec, s[54:55]
	v_mov_b64_e32 v[88:89], v[104:105]
	v_mov_b64_e32 v[84:85], v[100:101]
	s_cbranch_vccnz .LBB0_317
	s_lshr_b32 s15, s29, 6
	v_readlane_b32 s96, v255, 14
	s_add_i32 s15, s15, s96
	s_and_b32 s15, s15, 31
	v_mov_b32_e32 v0, s15
	v_cndmask_b32_e64 v0, v151, v0, s[38:39]
	v_lshlrev_b32_e32 v0, 7, v0
	v_lshl_add_u64 v[86:87], v[152:153], 0, v[0:1]
	global_load_dwordx4 v[82:85], v[86:87], off
	s_nop 0
	global_load_dwordx4 v[86:89], v[86:87], off offset:16

;     __device__ __forceinline__ void operator()(const f32x4 (&acc)[2][2][4][2], const Unit& u, int wr, int wc, int fr, int fq) const {
;     ...
;                     if (pn <= 1) {
; #pragma unroll
;                         for (int i = 0; i < 4; ++i) { v0[i] = gelu_tanh_f(v0[i]); v1[i] = gelu_tanh_f(v1[i]); }
;                         bf16_t* p = UV + (size_t)r * 512 + pn * 256 + ctb;
;                         *(u32x2*)p = (u32x2){cvt_pk_bf16(v0[0], v0[1]), cvt_pk_bf16(v0[2], v0[3])}; *(u32x2*)(p + 16) = (u32x2){cvt_pk_bf16(v1[0], v1[1]), cvt_pk_bf16(v1[2], v1[3])};
;                     } else if (pn <= 4) {
;                         v0 = v0 * QSCALE; v1 = v1 * QSCALE;
;                         bf16_t* p = (pn <= 3) ? QB + (size_t)r * 512 + (pn - 2) * 256 + ctb : QC + (size_t)r * 256 + ctb;
;                         *(u32x2*)p = (u32x2){cvt_pk_bf16(v0[0], v0[1]), cvt_pk_bf16(v0[2], v0[3])}; *(u32x2*)(p + 16) = (u32x2){cvt_pk_bf16(v1[0], v1[1]), cvt_pk_bf16(v1[2], v1[3])};
;                     } else if (pn <= 6) {
;                         const int ck = (pn - 5) * 256 + ctb, head = ck >> 7, cw = ck & 127;
;                         bf16_t* p = KB + ((size_t)(b * 4 + head) * NKEY + keyidx) * 128 + cw;
;                         *(u32x2*)p = (u32x2){cvt_pk_bf16(v0[0], v0[1]), cvt_pk_bf16(v0[2], v0[3])}; *(u32x2*)(p + 16) = (u32x2){cvt_pk_bf16(v1[0], v1[1]), cvt_pk_bf16(v1[2], v1[3])};
;                     } else if (pn <= 8) {
;                         const int cv = (pn - 7) * 256 + ctb, head = cv >> 7, e = cv & 127;
;                         bf16_t* p = VBt + ((size_t)(b * 4 + head) * NKEY + keyidx) * 128 + e;
;                         *(u32x2*)p = (u32x2){cvt_pk_bf16(v0[0], v0[1]), cvt_pk_bf16(v0[2], v0[3])}; *(u32x2*)(p + 16) = (u32x2){cvt_pk_bf16(v1[0], v1[1]), cvt_pk_bf16(v1[2], v1[3])};
;                     } else {
;                         const int kv = wc >> 1, d = (wc & 1) * 32 + 4 * fq;
;                         if (bj == 0) {
;                             bf16_t* p = KC + ((size_t)(b * 2 + kv) * NKEY + keyidx) * 64 + d;
;                             *(u32x2*)p = (u32x2){cvt_pk_bf16(v0[0], v0[1]), cvt_pk_bf16(v0[2], v0[3])}; *(u32x2*)(p + 16) = (u32x2){cvt_pk_bf16(v1[0], v1[1]), cvt_pk_bf16(v1[2], v1[3])};
;                         } else {
;                             bf16_t* p = VCt + ((size_t)(b * 2 + kv) * NKEY + keyidx) * 64 + d;
.LBB0_333:
	s_and_b64 vcc, exec, s[50:51]
	v_mov_b64_e32 v[218:219], v[108:109]
	s_nop 1
	v_permlane16_swap_b32_e32 v216, v218
	v_permlane16_swap_b32_e32 v217, v219
	v_lshl_add_u64 v[220:221], v[106:107], 0, v[222:223]
	global_store_dwordx4 v[220:221], v[216:219], off
	s_cbranch_vccnz .LBB0_335

; __device__ __forceinline__ unsigned cvt_pk_bf16(float lo, float hi) { unsigned r; asm volatile("v_cvt_pk_bf16_f32 %0, %1, %2" : "=v"(r) : "v"(lo), "v"(hi)); return r; }
; __device__ __forceinline__ float gelu_tanh_f(float x) { const float y = 1.5957691216057308f * (x + 0.044715f * x * x * x); return x * __builtin_amdgcn_rcpf(1.f + __expf(-y)); }
;     __device__ __forceinline__ void operator()(const f32x4 (&acc)[2][2][4][2], const Unit& u, int wr, int wc, int fr, int fq) const {
;     ...
;                     if (pn <= 1) {
; #pragma unroll
;                         for (int i = 0; i < 4; ++i) { v0[i] = gelu_tanh_f(v0[i]); v1[i] = gelu_tanh_f(v1[i]); }
;                         bf16_t* p = UV + (size_t)r * 512 + pn * 256 + ctb;
;                         *(u32x2*)p = (u32x2){cvt_pk_bf16(v0[0], v0[1]), cvt_pk_bf16(v0[2], v0[3])}; *(u32x2*)(p + 16) = (u32x2){cvt_pk_bf16(v1[0], v1[1]), cvt_pk_bf16(v1[2], v1[3])};
.LBB0_350:
	v_mul_f32_e32 v106, 0x3d372713, v78
	v_mul_f32_e32 v106, v78, v106
	v_fma_f32 v106, v78, v106, v78
	v_mul_f32_e32 v106, 0xbfcc422a, v106
	v_mul_f32_e32 v106, 0x3fb8aa3b, v106
	v_exp_f32_e32 v106, v106
	v_mov_b32_e32 v169, v1
	v_add_f32_e32 v106, 1.0, v106
	v_rcp_f32_e32 v106, v106
	s_nop 0
	v_mul_f32_e32 v78, v78, v106
	v_mul_f32_e32 v106, 0x3d372713, v74
	v_mul_f32_e32 v106, v74, v106
	v_fma_f32 v106, v74, v106, v74
	v_mul_f32_e32 v106, 0xbfcc422a, v106
	v_mul_f32_e32 v106, 0x3fb8aa3b, v106
	v_exp_f32_e32 v106, v106
	s_nop 0
	v_add_f32_e32 v106, 1.0, v106
	v_rcp_f32_e32 v106, v106
	s_nop 0
	v_mul_f32_e32 v108, v74, v106
	v_mul_f32_e32 v74, 0x3d372713, v79
	v_mul_f32_e32 v74, v79, v74
	v_fma_f32 v74, v79, v74, v79
	v_mul_f32_e32 v74, 0xbfcc422a, v74
	v_mul_f32_e32 v74, 0x3fb8aa3b, v74
	v_exp_f32_e32 v74, v74
	v_lshl_add_u64 v[106:107], v[90:91], 0, v[168:169]
	v_add_f32_e32 v74, 1.0, v74
	v_rcp_f32_e32 v74, v74
	s_nop 0
	v_mul_f32_e32 v74, v79, v74
	v_mul_f32_e32 v79, 0x3d372713, v75
	v_mul_f32_e32 v79, v75, v79
	v_fma_f32 v79, v75, v79, v75
	v_mul_f32_e32 v79, 0xbfcc422a, v79
	v_mul_f32_e32 v79, 0x3fb8aa3b, v79
	v_exp_f32_e32 v79, v79
	v_cvt_pk_bf16_f32 v74, v78, v74
	s_nop 0
	v_add_f32_e32 v79, 1.0, v79
	v_rcp_f32_e32 v79, v79
	s_nop 0
	v_mul_f32_e32 v79, v75, v79
	v_mul_f32_e32 v75, 0x3d372713, v80
	v_mul_f32_e32 v75, v80, v75
	v_fma_f32 v75, v80, v75, v80
	v_mul_f32_e32 v75, 0xbfcc422a, v75
	v_mul_f32_e32 v75, 0x3fb8aa3b, v75
	v_exp_f32_e32 v75, v75
	s_nop 0
	v_add_f32_e32 v75, 1.0, v75
	v_rcp_f32_e32 v75, v75
	s_nop 0
	v_mul_f32_e32 v75, v80, v75
	v_mul_f32_e32 v80, 0x3d372713, v76
	v_mul_f32_e32 v80, v76, v80
	v_fma_f32 v80, v76, v80, v76
	v_mul_f32_e32 v80, 0xbfcc422a, v80
	v_mul_f32_e32 v80, 0x3fb8aa3b, v80
	v_exp_f32_e32 v80, v80
	s_nop 0
	v_add_f32_e32 v80, 1.0, v80
	v_rcp_f32_e32 v80, v80
	s_nop 0
	v_mul_f32_e32 v76, v76, v80
	v_mul_f32_e32 v80, 0x3d372713, v81
	v_mul_f32_e32 v80, v81, v80
	v_fma_f32 v80, v81, v80, v81
	v_mul_f32_e32 v80, 0xbfcc422a, v80
	v_mul_f32_e32 v80, 0x3fb8aa3b, v80
	v_exp_f32_e32 v80, v80
	s_nop 0
	v_add_f32_e32 v80, 1.0, v80
	v_rcp_f32_e32 v80, v80
	s_nop 0
	v_mul_f32_e32 v80, v81, v80
	v_mul_f32_e32 v81, 0x3d372713, v77
	v_mul_f32_e32 v81, v77, v81
	v_fma_f32 v81, v77, v81, v77
	v_mul_f32_e32 v81, 0xbfcc422a, v81
	v_mul_f32_e32 v81, 0x3fb8aa3b, v81
	v_exp_f32_e32 v81, v81
	v_cvt_pk_bf16_f32 v75, v75, v80
	v_mov_b64_e32 v[216:217], v[74:75]
	v_cvt_pk_bf16_f32 v108, v108, v79
	v_add_f32_e32 v81, 1.0, v81
	v_rcp_f32_e32 v81, v81
	s_nop 0
	v_mul_f32_e32 v77, v77, v81
	v_cvt_pk_bf16_f32 v109, v76, v77
	s_and_b64 vcc, exec, s[50:51]
	v_mov_b64_e32 v[218:219], v[108:109]
	s_nop 1
	v_permlane16_swap_b32_e32 v216, v218
	v_permlane16_swap_b32_e32 v217, v219
	v_lshl_add_u64 v[220:221], v[106:107], 0, v[222:223]
	global_store_dwordx4 v[220:221], v[216:219], off
	s_cbranch_vccnz .LBB0_335
	s_branch .LBB0_334

; #define ROPE_FETCH(ai_, m_) do { const int s_ = (u.pm * BM + (ai_) * HALF + wr * 64 + (m_) * 16 + fr) & 2047, pos_ = (wc & 1) ? (s_ & 63) : (s_ >> 6); \
;             n01 = *(const f32x4*)(rope + pos_ * 16 + 4 * fq); n23 = *(const f32x4*)(rope + pos_ * 16 + 4 * fq + 2); } while (0)
;     __device__ __forceinline__ void operator()(const f32x4 (&acc)[2][2][4][2], const Unit& u, int wr, int wc, int fr, int fq) const {
;     ...
;         if (do_rope) ROPE_FETCH(0, 0);
; #pragma unroll
;         for (int ai = 0; ai < 2; ++ai)
; #pragma unroll
;             for (int m = 0; m < 4; ++m) {
;                 const f32x4 c01 = n01, c23 = n23;
;                 if (do_rope && (ai * 4 + m) < 7) ROPE_FETCH((ai * 4 + m + 1) >> 2, (ai * 4 + m + 1) & 3);
.LBB0_353:
	v_mov_b64_e32 v[218:219], v[76:77]
	s_nop 1
	v_permlane16_swap_b32_e32 v216, v218
	v_permlane16_swap_b32_e32 v217, v219
	v_lshl_add_u64 v[220:221], v[74:75], 0, v[222:223]
	global_store_dwordx4 v[220:221], v[216:219], off
	s_waitcnt vmcnt(0) lgkmcnt(0)
	v_mov_b64_e32 v[70:71], v[86:87]
	v_mov_b64_e32 v[66:67], v[82:83]
	s_and_b64 vcc, exec, s[54:55]
	v_mov_b64_e32 v[72:73], v[88:89]
	v_mov_b64_e32 v[68:69], v[84:85]
	s_cbranch_vccnz .LBB0_355
	s_lshr_b32 s3, s29, 6
	v_readlane_b32 s14, v255, 14
	s_add_i32 s3, s3, s14
	s_and_b32 s3, s3, 31
	v_mov_b32_e32 v0, s3
	v_cndmask_b32_e64 v0, v208, v0, s[38:39]
	v_lshlrev_b32_e32 v0, 7, v0
	v_lshl_add_u64 v[70:71], v[152:153], 0, v[0:1]
	global_load_dwordx4 v[66:69], v[70:71], off
	s_nop 0
	global_load_dwordx4 v[70:73], v[70:71], off offset:16

;     __device__ __forceinline__ void operator()(const f32x4 (&acc)[2][2][4][2], const Unit& u, int wr, int wc, int fr, int fq) const {
;     ...
;                     if (pn <= 1) {
; #pragma unroll
;                         for (int i = 0; i < 4; ++i) { v0[i] = gelu_tanh_f(v0[i]); v1[i] = gelu_tanh_f(v1[i]); }
;                         bf16_t* p = UV + (size_t)r * 512 + pn * 256 + ctb;
;                         *(u32x2*)p = (u32x2){cvt_pk_bf16(v0[0], v0[1]), cvt_pk_bf16(v0[2], v0[3])}; *(u32x2*)(p + 16) = (u32x2){cvt_pk_bf16(v1[0], v1[1]), cvt_pk_bf16(v1[2], v1[3])};
;                     } else if (pn <= 4) {
;                         v0 = v0 * QSCALE; v1 = v1 * QSCALE;
;                         bf16_t* p = (pn <= 3) ? QB + (size_t)r * 512 + (pn - 2) * 256 + ctb : QC + (size_t)r * 256 + ctb;
;                         *(u32x2*)p = (u32x2){cvt_pk_bf16(v0[0], v0[1]), cvt_pk_bf16(v0[2], v0[3])}; *(u32x2*)(p + 16) = (u32x2){cvt_pk_bf16(v1[0], v1[1]), cvt_pk_bf16(v1[2], v1[3])};
;                     } else if (pn <= 6) {
;                         const int ck = (pn - 5) * 256 + ctb, head = ck >> 7, cw = ck & 127;
;                         bf16_t* p = KB + ((size_t)(b * 4 + head) * NKEY + keyidx) * 128 + cw;
;                         *(u32x2*)p = (u32x2){cvt_pk_bf16(v0[0], v0[1]), cvt_pk_bf16(v0[2], v0[3])}; *(u32x2*)(p + 16) = (u32x2){cvt_pk_bf16(v1[0], v1[1]), cvt_pk_bf16(v1[2], v1[3])};
;                     } else if (pn <= 8) {
;                         const int cv = (pn - 7) * 256 + ctb, head = cv >> 7, e = cv & 127;
;                         bf16_t* p = VBt + ((size_t)(b * 4 + head) * NKEY + keyidx) * 128 + e;
;                         *(u32x2*)p = (u32x2){cvt_pk_bf16(v0[0], v0[1]), cvt_pk_bf16(v0[2], v0[3])}; *(u32x2*)(p + 16) = (u32x2){cvt_pk_bf16(v1[0], v1[1]), cvt_pk_bf16(v1[2], v1[3])};
;                     } else {
;                         const int kv = wc >> 1, d = (wc & 1) * 32 + 4 * fq;
;                         if (bj == 0) {
;                             bf16_t* p = KC + ((size_t)(b * 2 + kv) * NKEY + keyidx) * 64 + d;
;                             *(u32x2*)p = (u32x2){cvt_pk_bf16(v0[0], v0[1]), cvt_pk_bf16(v0[2], v0[3])}; *(u32x2*)(p + 16) = (u32x2){cvt_pk_bf16(v1[0], v1[1]), cvt_pk_bf16(v1[2], v1[3])};
;                         } else {
;                             bf16_t* p = VCt + ((size_t)(b * 2 + kv) * NKEY + keyidx) * 64 + d;
.LBB0_371:
	s_and_b64 vcc, exec, s[50:51]
	v_mov_b64_e32 v[218:219], v[94:95]
	s_nop 1
	v_permlane16_swap_b32_e32 v216, v218
	v_permlane16_swap_b32_e32 v217, v219
	v_lshl_add_u64 v[220:221], v[92:93], 0, v[222:223]
	global_store_dwordx4 v[220:221], v[216:219], off
	s_cbranch_vccnz .LBB0_373

; __device__ __forceinline__ unsigned cvt_pk_bf16(float lo, float hi) { unsigned r; asm volatile("v_cvt_pk_bf16_f32 %0, %1, %2" : "=v"(r) : "v"(lo), "v"(hi)); return r; }
; __device__ __forceinline__ float gelu_tanh_f(float x) { const float y = 1.5957691216057308f * (x + 0.044715f * x * x * x); return x * __builtin_amdgcn_rcpf(1.f + __expf(-y)); }
;     __device__ __forceinline__ void operator()(const f32x4 (&acc)[2][2][4][2], const Unit& u, int wr, int wc, int fr, int fq) const {
;     ...
;                     if (pn <= 1) {
; #pragma unroll
;                         for (int i = 0; i < 4; ++i) { v0[i] = gelu_tanh_f(v0[i]); v1[i] = gelu_tanh_f(v1[i]); }
;                         bf16_t* p = UV + (size_t)r * 512 + pn * 256 + ctb;
;                         *(u32x2*)p = (u32x2){cvt_pk_bf16(v0[0], v0[1]), cvt_pk_bf16(v0[2], v0[3])}; *(u32x2*)(p + 16) = (u32x2){cvt_pk_bf16(v1[0], v1[1]), cvt_pk_bf16(v1[2], v1[3])};
.LBB0_388:
	v_mul_f32_e32 v75, 0x3d372713, v62
	v_mul_f32_e32 v75, v62, v75
	v_fma_f32 v75, v62, v75, v62
	v_mul_f32_e32 v75, 0xbfcc422a, v75
	v_mul_f32_e32 v75, 0x3fb8aa3b, v75
	v_exp_f32_e32 v75, v75
	v_mov_b32_e32 v169, v1
	v_lshl_add_u64 v[92:93], v[76:77], 0, v[168:169]
	v_add_f32_e32 v75, 1.0, v75
	v_rcp_f32_e32 v75, v75
	s_nop 0
	v_mul_f32_e32 v62, v62, v75
	v_mul_f32_e32 v75, 0x3d372713, v58
	v_mul_f32_e32 v75, v58, v75
	v_fma_f32 v75, v58, v75, v58
	v_mul_f32_e32 v75, 0xbfcc422a, v75
	v_mul_f32_e32 v75, 0x3fb8aa3b, v75
	v_exp_f32_e32 v75, v75
	s_nop 0
	v_add_f32_e32 v75, 1.0, v75
	v_rcp_f32_e32 v75, v75
	s_nop 0
	v_mul_f32_e32 v75, v58, v75
	v_mul_f32_e32 v58, 0x3d372713, v63
	v_mul_f32_e32 v58, v63, v58
	v_fma_f32 v58, v63, v58, v63
	v_mul_f32_e32 v58, 0xbfcc422a, v58
	v_mul_f32_e32 v58, 0x3fb8aa3b, v58
	v_exp_f32_e32 v58, v58
	s_nop 0
	v_add_f32_e32 v58, 1.0, v58
	v_rcp_f32_e32 v58, v58
	s_nop 0
	v_mul_f32_e32 v58, v63, v58
	v_mul_f32_e32 v63, 0x3d372713, v59
	v_mul_f32_e32 v63, v59, v63
	v_fma_f32 v63, v59, v63, v59
	v_mul_f32_e32 v63, 0xbfcc422a, v63
	v_mul_f32_e32 v63, 0x3fb8aa3b, v63
	v_exp_f32_e32 v63, v63
	v_cvt_pk_bf16_f32 v58, v62, v58
	s_nop 0
	v_add_f32_e32 v63, 1.0, v63
	v_rcp_f32_e32 v63, v63
	s_nop 0
	v_mul_f32_e32 v63, v59, v63
	v_mul_f32_e32 v59, 0x3d372713, v64
	v_mul_f32_e32 v59, v64, v59
	v_fma_f32 v59, v64, v59, v64
	v_mul_f32_e32 v59, 0xbfcc422a, v59
	v_mul_f32_e32 v59, 0x3fb8aa3b, v59
	v_exp_f32_e32 v59, v59
	s_nop 0
	v_add_f32_e32 v59, 1.0, v59
	v_rcp_f32_e32 v59, v59
	s_nop 0
	v_mul_f32_e32 v59, v64, v59
	v_mul_f32_e32 v64, 0x3d372713, v60
	v_mul_f32_e32 v64, v60, v64
	v_fma_f32 v64, v60, v64, v60
	v_mul_f32_e32 v64, 0xbfcc422a, v64
	v_mul_f32_e32 v64, 0x3fb8aa3b, v64
	v_exp_f32_e32 v64, v64
	s_nop 0
	v_add_f32_e32 v64, 1.0, v64
	v_rcp_f32_e32 v64, v64
	s_nop 0
	v_mul_f32_e32 v60, v60, v64
	v_mul_f32_e32 v64, 0x3d372713, v65
	v_mul_f32_e32 v64, v65, v64
	v_fma_f32 v64, v65, v64, v65
	v_mul_f32_e32 v64, 0xbfcc422a, v64
	v_mul_f32_e32 v64, 0x3fb8aa3b, v64
	v_exp_f32_e32 v64, v64
	s_nop 0
	v_add_f32_e32 v64, 1.0, v64
	v_rcp_f32_e32 v64, v64
	s_nop 0
	v_mul_f32_e32 v64, v65, v64
	v_mul_f32_e32 v65, 0x3d372713, v61
	v_mul_f32_e32 v65, v61, v65
	v_fma_f32 v65, v61, v65, v61
	v_mul_f32_e32 v65, 0xbfcc422a, v65
	v_mul_f32_e32 v65, 0x3fb8aa3b, v65
	v_exp_f32_e32 v65, v65
	v_cvt_pk_bf16_f32 v59, v59, v64
	v_mov_b64_e32 v[216:217], v[58:59]
	v_cvt_pk_bf16_f32 v94, v75, v63
	v_add_f32_e32 v65, 1.0, v65
	v_rcp_f32_e32 v65, v65
	s_nop 0
	v_mul_f32_e32 v61, v61, v65
	v_cvt_pk_bf16_f32 v95, v60, v61
	s_and_b64 vcc, exec, s[50:51]
	v_mov_b64_e32 v[218:219], v[94:95]
	s_nop 1
	v_permlane16_swap_b32_e32 v216, v218
	v_permlane16_swap_b32_e32 v217, v219
	v_lshl_add_u64 v[220:221], v[92:93], 0, v[222:223]
	global_store_dwordx4 v[220:221], v[216:219], off
	s_cbranch_vccnz .LBB0_373
	s_branch .LBB0_372

; #define ROPE_FETCH(ai_, m_) do { const int s_ = (u.pm * BM + (ai_) * HALF + wr * 64 + (m_) * 16 + fr) & 2047, pos_ = (wc & 1) ? (s_ & 63) : (s_ >> 6); \
;             n01 = *(const f32x4*)(rope + pos_ * 16 + 4 * fq); n23 = *(const f32x4*)(rope + pos_ * 16 + 4 * fq + 2); } while (0)
;     __device__ __forceinline__ void operator()(const f32x4 (&acc)[2][2][4][2], const Unit& u, int wr, int wc, int fr, int fq) const {
;     ...
;         if (do_rope) ROPE_FETCH(0, 0);
; #pragma unroll
;         for (int ai = 0; ai < 2; ++ai)
; #pragma unroll
;             for (int m = 0; m < 4; ++m) {
;                 const f32x4 c01 = n01, c23 = n23;
;                 if (do_rope && (ai * 4 + m) < 7) ROPE_FETCH((ai * 4 + m + 1) >> 2, (ai * 4 + m + 1) & 3);
.LBB0_391:
	v_mov_b64_e32 v[218:219], v[60:61]
	s_nop 1
	v_permlane16_swap_b32_e32 v216, v218
	v_permlane16_swap_b32_e32 v217, v219
	v_lshl_add_u64 v[220:221], v[58:59], 0, v[222:223]
	global_store_dwordx4 v[220:221], v[216:219], off
	s_waitcnt vmcnt(0) lgkmcnt(0)
	v_mov_b64_e32 v[54:55], v[70:71]
	v_mov_b64_e32 v[50:51], v[66:67]
	s_and_b64 vcc, exec, s[54:55]
	v_mov_b64_e32 v[56:57], v[72:73]
	v_mov_b64_e32 v[52:53], v[68:69]
	s_cbranch_vccnz .LBB0_393
	s_lshr_b32 s18, s29, 6
	v_readlane_b32 s19, v255, 14
	s_add_i32 s18, s18, s19
	s_and_b32 s18, s18, 31
	v_mov_b32_e32 v0, s18
	v_cndmask_b32_e64 v0, v209, v0, s[38:39]
	v_lshlrev_b32_e32 v0, 7, v0
	v_lshl_add_u64 v[54:55], v[152:153], 0, v[0:1]
	global_load_dwordx4 v[50:53], v[54:55], off
	s_nop 0
	global_load_dwordx4 v[54:57], v[54:55], off offset:16

;     __device__ __forceinline__ void operator()(const f32x4 (&acc)[2][2][4][2], const Unit& u, int wr, int wc, int fr, int fq) const {
;     ...
;                     if (pn <= 1) {
; #pragma unroll
;                         for (int i = 0; i < 4; ++i) { v0[i] = gelu_tanh_f(v0[i]); v1[i] = gelu_tanh_f(v1[i]); }
;                         bf16_t* p = UV + (size_t)r * 512 + pn * 256 + ctb;
;                         *(u32x2*)p = (u32x2){cvt_pk_bf16(v0[0], v0[1]), cvt_pk_bf16(v0[2], v0[3])}; *(u32x2*)(p + 16) = (u32x2){cvt_pk_bf16(v1[0], v1[1]), cvt_pk_bf16(v1[2], v1[3])};
;                     } else if (pn <= 4) {
;                         v0 = v0 * QSCALE; v1 = v1 * QSCALE;
;                         bf16_t* p = (pn <= 3) ? QB + (size_t)r * 512 + (pn - 2) * 256 + ctb : QC + (size_t)r * 256 + ctb;
;                         *(u32x2*)p = (u32x2){cvt_pk_bf16(v0[0], v0[1]), cvt_pk_bf16(v0[2], v0[3])}; *(u32x2*)(p + 16) = (u32x2){cvt_pk_bf16(v1[0], v1[1]), cvt_pk_bf16(v1[2], v1[3])};
;                     } else if (pn <= 6) {
;                         const int ck = (pn - 5) * 256 + ctb, head = ck >> 7, cw = ck & 127;
;                         bf16_t* p = KB + ((size_t)(b * 4 + head) * NKEY + keyidx) * 128 + cw;
;                         *(u32x2*)p = (u32x2){cvt_pk_bf16(v0[0], v0[1]), cvt_pk_bf16(v0[2], v0[3])}; *(u32x2*)(p + 16) = (u32x2){cvt_pk_bf16(v1[0], v1[1]), cvt_pk_bf16(v1[2], v1[3])};
;                     } else if (pn <= 8) {
;                         const int cv = (pn - 7) * 256 + ctb, head = cv >> 7, e = cv & 127;
;                         bf16_t* p = VBt + ((size_t)(b * 4 + head) * NKEY + keyidx) * 128 + e;
;                         *(u32x2*)p = (u32x2){cvt_pk_bf16(v0[0], v0[1]), cvt_pk_bf16(v0[2], v0[3])}; *(u32x2*)(p + 16) = (u32x2){cvt_pk_bf16(v1[0], v1[1]), cvt_pk_bf16(v1[2], v1[3])};
;                     } else {
;                         const int kv = wc >> 1, d = (wc & 1) * 32 + 4 * fq;
;                         if (bj == 0) {
;                             bf16_t* p = KC + ((size_t)(b * 2 + kv) * NKEY + keyidx) * 64 + d;
;                             *(u32x2*)p = (u32x2){cvt_pk_bf16(v0[0], v0[1]), cvt_pk_bf16(v0[2], v0[3])}; *(u32x2*)(p + 16) = (u32x2){cvt_pk_bf16(v1[0], v1[1]), cvt_pk_bf16(v1[2], v1[3])};
;                         } else {
;                             bf16_t* p = VCt + ((size_t)(b * 2 + kv) * NKEY + keyidx) * 64 + d;
.LBB0_409:
	s_and_b64 vcc, exec, s[50:51]
	v_mov_b64_e32 v[218:219], v[78:79]
	s_nop 1
	v_permlane16_swap_b32_e32 v216, v218
	v_permlane16_swap_b32_e32 v217, v219
	v_lshl_add_u64 v[220:221], v[76:77], 0, v[222:223]
	global_store_dwordx4 v[220:221], v[216:219], off
	s_cbranch_vccnz .LBB0_411

; __device__ __forceinline__ unsigned cvt_pk_bf16(float lo, float hi) { unsigned r; asm volatile("v_cvt_pk_bf16_f32 %0, %1, %2" : "=v"(r) : "v"(lo), "v"(hi)); return r; }
; __device__ __forceinline__ float gelu_tanh_f(float x) { const float y = 1.5957691216057308f * (x + 0.044715f * x * x * x); return x * __builtin_amdgcn_rcpf(1.f + __expf(-y)); }
;     __device__ __forceinline__ void operator()(const f32x4 (&acc)[2][2][4][2], const Unit& u, int wr, int wc, int fr, int fq) const {
;     ...
;                     if (pn <= 1) {
; #pragma unroll
;                         for (int i = 0; i < 4; ++i) { v0[i] = gelu_tanh_f(v0[i]); v1[i] = gelu_tanh_f(v1[i]); }
;                         bf16_t* p = UV + (size_t)r * 512 + pn * 256 + ctb;
;                         *(u32x2*)p = (u32x2){cvt_pk_bf16(v0[0], v0[1]), cvt_pk_bf16(v0[2], v0[3])}; *(u32x2*)(p + 16) = (u32x2){cvt_pk_bf16(v1[0], v1[1]), cvt_pk_bf16(v1[2], v1[3])};
.LBB0_426:
	v_mul_f32_e32 v75, 0x3d372713, v46
	v_mul_f32_e32 v75, v46, v75
	v_fma_f32 v75, v46, v75, v46
	v_mul_f32_e32 v75, 0xbfcc422a, v75
	v_mul_f32_e32 v75, 0x3fb8aa3b, v75
	v_exp_f32_e32 v75, v75
	v_mov_b32_e32 v169, v1
	v_lshl_add_u64 v[76:77], v[58:59], 0, v[168:169]
	v_add_f32_e32 v75, 1.0, v75
	v_rcp_f32_e32 v75, v75
	s_nop 0
	v_mul_f32_e32 v46, v46, v75
	v_mul_f32_e32 v75, 0x3d372713, v42
	v_mul_f32_e32 v75, v42, v75
	v_fma_f32 v75, v42, v75, v42
	v_mul_f32_e32 v75, 0xbfcc422a, v75
	v_mul_f32_e32 v75, 0x3fb8aa3b, v75
	v_exp_f32_e32 v75, v75
	s_nop 0
	v_add_f32_e32 v75, 1.0, v75
	v_rcp_f32_e32 v75, v75
	s_nop 0
	v_mul_f32_e32 v75, v42, v75
	v_mul_f32_e32 v42, 0x3d372713, v47
	v_mul_f32_e32 v42, v47, v42
	v_fma_f32 v42, v47, v42, v47
	v_mul_f32_e32 v42, 0xbfcc422a, v42
	v_mul_f32_e32 v42, 0x3fb8aa3b, v42
	v_exp_f32_e32 v42, v42
	s_nop 0
	v_add_f32_e32 v42, 1.0, v42
	v_rcp_f32_e32 v42, v42
	s_nop 0
	v_mul_f32_e32 v42, v47, v42
	v_mul_f32_e32 v47, 0x3d372713, v43
	v_mul_f32_e32 v47, v43, v47
	v_fma_f32 v47, v43, v47, v43
	v_mul_f32_e32 v47, 0xbfcc422a, v47
	v_mul_f32_e32 v47, 0x3fb8aa3b, v47
	v_exp_f32_e32 v47, v47
	v_cvt_pk_bf16_f32 v42, v46, v42
	s_nop 0
	v_add_f32_e32 v47, 1.0, v47
	v_rcp_f32_e32 v47, v47
	s_nop 0
	v_mul_f32_e32 v47, v43, v47
	v_mul_f32_e32 v43, 0x3d372713, v48
	v_mul_f32_e32 v43, v48, v43
	v_fma_f32 v43, v48, v43, v48
	v_mul_f32_e32 v43, 0xbfcc422a, v43
	v_mul_f32_e32 v43, 0x3fb8aa3b, v43
	v_exp_f32_e32 v43, v43
	s_nop 0
	v_add_f32_e32 v43, 1.0, v43
	v_rcp_f32_e32 v43, v43
	s_nop 0
	v_mul_f32_e32 v43, v48, v43
	v_mul_f32_e32 v48, 0x3d372713, v44
	v_mul_f32_e32 v48, v44, v48
	v_fma_f32 v48, v44, v48, v44
	v_mul_f32_e32 v48, 0xbfcc422a, v48
	v_mul_f32_e32 v48, 0x3fb8aa3b, v48
	v_exp_f32_e32 v48, v48
	s_nop 0
	v_add_f32_e32 v48, 1.0, v48
	v_rcp_f32_e32 v48, v48
	s_nop 0
	v_mul_f32_e32 v44, v44, v48
	v_mul_f32_e32 v48, 0x3d372713, v49
	v_mul_f32_e32 v48, v49, v48
	v_fma_f32 v48, v49, v48, v49
	v_mul_f32_e32 v48, 0xbfcc422a, v48
	v_mul_f32_e32 v48, 0x3fb8aa3b, v48
	v_exp_f32_e32 v48, v48
	s_nop 0
	v_add_f32_e32 v48, 1.0, v48
	v_rcp_f32_e32 v48, v48
	s_nop 0
	v_mul_f32_e32 v48, v49, v48
	v_mul_f32_e32 v49, 0x3d372713, v45
	v_mul_f32_e32 v49, v45, v49
	v_fma_f32 v49, v45, v49, v45
	v_mul_f32_e32 v49, 0xbfcc422a, v49
	v_mul_f32_e32 v49, 0x3fb8aa3b, v49
	v_exp_f32_e32 v49, v49
	v_cvt_pk_bf16_f32 v43, v43, v48
	v_mov_b64_e32 v[216:217], v[42:43]
	v_cvt_pk_bf16_f32 v78, v75, v47
	v_add_f32_e32 v49, 1.0, v49
	v_rcp_f32_e32 v49, v49
	s_nop 0
	v_mul_f32_e32 v45, v45, v49
	v_cvt_pk_bf16_f32 v79, v44, v45
	s_and_b64 vcc, exec, s[50:51]
	v_mov_b64_e32 v[218:219], v[78:79]
	s_nop 1
	v_permlane16_swap_b32_e32 v216, v218
	v_permlane16_swap_b32_e32 v217, v219
	v_lshl_add_u64 v[220:221], v[76:77], 0, v[222:223]
	global_store_dwordx4 v[220:221], v[216:219], off
	s_cbranch_vccnz .LBB0_411
	s_branch .LBB0_410

; #define ROPE_FETCH(ai_, m_) do { const int s_ = (u.pm * BM + (ai_) * HALF + wr * 64 + (m_) * 16 + fr) & 2047, pos_ = (wc & 1) ? (s_ & 63) : (s_ >> 6); \
;             n01 = *(const f32x4*)(rope + pos_ * 16 + 4 * fq); n23 = *(const f32x4*)(rope + pos_ * 16 + 4 * fq + 2); } while (0)
;     __device__ __forceinline__ void operator()(const f32x4 (&acc)[2][2][4][2], const Unit& u, int wr, int wc, int fr, int fq) const {
;     ...
;         if (do_rope) ROPE_FETCH(0, 0);
; #pragma unroll
;         for (int ai = 0; ai < 2; ++ai)
; #pragma unroll
;             for (int m = 0; m < 4; ++m) {
;                 const f32x4 c01 = n01, c23 = n23;
;                 if (do_rope && (ai * 4 + m) < 7) ROPE_FETCH((ai * 4 + m + 1) >> 2, (ai * 4 + m + 1) & 3);
.LBB0_429:
	v_mov_b64_e32 v[218:219], v[44:45]
	s_nop 1
	v_permlane16_swap_b32_e32 v216, v218
	v_permlane16_swap_b32_e32 v217, v219
	v_lshl_add_u64 v[220:221], v[42:43], 0, v[222:223]
	global_store_dwordx4 v[220:221], v[216:219], off
	s_waitcnt vmcnt(0) lgkmcnt(0)
	v_mov_b64_e32 v[38:39], v[54:55]
	v_mov_b64_e32 v[34:35], v[50:51]
	s_and_b64 vcc, exec, s[54:55]
	v_mov_b64_e32 v[40:41], v[56:57]
	v_mov_b64_e32 v[36:37], v[52:53]
	s_cbranch_vccnz .LBB0_431
	s_lshr_b32 s15, s29, 6
	v_readlane_b32 s25, v255, 14
	s_add_i32 s15, s15, s25
	s_and_b32 s15, s15, 31
	v_mov_b32_e32 v0, s15
	v_cndmask_b32_e64 v0, v210, v0, s[38:39]
	v_lshlrev_b32_e32 v0, 7, v0
	v_lshl_add_u64 v[38:39], v[152:153], 0, v[0:1]
	global_load_dwordx4 v[34:37], v[38:39], off
	s_nop 0
	global_load_dwordx4 v[38:41], v[38:39], off offset:16

;     __device__ __forceinline__ void operator()(const f32x4 (&acc)[2][2][4][2], const Unit& u, int wr, int wc, int fr, int fq) const {
;     ...
;                     if (pn <= 1) {
; #pragma unroll
;                         for (int i = 0; i < 4; ++i) { v0[i] = gelu_tanh_f(v0[i]); v1[i] = gelu_tanh_f(v1[i]); }
;                         bf16_t* p = UV + (size_t)r * 512 + pn * 256 + ctb;
;                         *(u32x2*)p = (u32x2){cvt_pk_bf16(v0[0], v0[1]), cvt_pk_bf16(v0[2], v0[3])}; *(u32x2*)(p + 16) = (u32x2){cvt_pk_bf16(v1[0], v1[1]), cvt_pk_bf16(v1[2], v1[3])};
;                     } else if (pn <= 4) {
;                         v0 = v0 * QSCALE; v1 = v1 * QSCALE;
;                         bf16_t* p = (pn <= 3) ? QB + (size_t)r * 512 + (pn - 2) * 256 + ctb : QC + (size_t)r * 256 + ctb;
;                         *(u32x2*)p = (u32x2){cvt_pk_bf16(v0[0], v0[1]), cvt_pk_bf16(v0[2], v0[3])}; *(u32x2*)(p + 16) = (u32x2){cvt_pk_bf16(v1[0], v1[1]), cvt_pk_bf16(v1[2], v1[3])};
;                     } else if (pn <= 6) {
;                         const int ck = (pn - 5) * 256 + ctb, head = ck >> 7, cw = ck & 127;
;                         bf16_t* p = KB + ((size_t)(b * 4 + head) * NKEY + keyidx) * 128 + cw;
;                         *(u32x2*)p = (u32x2){cvt_pk_bf16(v0[0], v0[1]), cvt_pk_bf16(v0[2], v0[3])}; *(u32x2*)(p + 16) = (u32x2){cvt_pk_bf16(v1[0], v1[1]), cvt_pk_bf16(v1[2], v1[3])};
;                     } else if (pn <= 8) {
;                         const int cv = (pn - 7) * 256 + ctb, head = cv >> 7, e = cv & 127;
;                         bf16_t* p = VBt + ((size_t)(b * 4 + head) * NKEY + keyidx) * 128 + e;
;                         *(u32x2*)p = (u32x2){cvt_pk_bf16(v0[0], v0[1]), cvt_pk_bf16(v0[2], v0[3])}; *(u32x2*)(p + 16) = (u32x2){cvt_pk_bf16(v1[0], v1[1]), cvt_pk_bf16(v1[2], v1[3])};
;                     } else {
;                         const int kv = wc >> 1, d = (wc & 1) * 32 + 4 * fq;
;                         if (bj == 0) {
;                             bf16_t* p = KC + ((size_t)(b * 2 + kv) * NKEY + keyidx) * 64 + d;
;                             *(u32x2*)p = (u32x2){cvt_pk_bf16(v0[0], v0[1]), cvt_pk_bf16(v0[2], v0[3])}; *(u32x2*)(p + 16) = (u32x2){cvt_pk_bf16(v1[0], v1[1]), cvt_pk_bf16(v1[2], v1[3])};
;                         } else {
;                             bf16_t* p = VCt + ((size_t)(b * 2 + kv) * NKEY + keyidx) * 64 + d;
.LBB0_447:
	s_and_b64 vcc, exec, s[50:51]
	v_mov_b64_e32 v[218:219], v[60:61]
	s_nop 1
	v_permlane16_swap_b32_e32 v216, v218
	v_permlane16_swap_b32_e32 v217, v219
	v_lshl_add_u64 v[220:221], v[58:59], 0, v[222:223]
	global_store_dwordx4 v[220:221], v[216:219], off
	s_cbranch_vccnz .LBB0_449

; __device__ __forceinline__ unsigned cvt_pk_bf16(float lo, float hi) { unsigned r; asm volatile("v_cvt_pk_bf16_f32 %0, %1, %2" : "=v"(r) : "v"(lo), "v"(hi)); return r; }
; __device__ __forceinline__ float gelu_tanh_f(float x) { const float y = 1.5957691216057308f * (x + 0.044715f * x * x * x); return x * __builtin_amdgcn_rcpf(1.f + __expf(-y)); }
;     __device__ __forceinline__ void operator()(const f32x4 (&acc)[2][2][4][2], const Unit& u, int wr, int wc, int fr, int fq) const {
;     ...
;                     if (pn <= 1) {
; #pragma unroll
;                         for (int i = 0; i < 4; ++i) { v0[i] = gelu_tanh_f(v0[i]); v1[i] = gelu_tanh_f(v1[i]); }
;                         bf16_t* p = UV + (size_t)r * 512 + pn * 256 + ctb;
;                         *(u32x2*)p = (u32x2){cvt_pk_bf16(v0[0], v0[1]), cvt_pk_bf16(v0[2], v0[3])}; *(u32x2*)(p + 16) = (u32x2){cvt_pk_bf16(v1[0], v1[1]), cvt_pk_bf16(v1[2], v1[3])};
.LBB0_464:
	v_mul_f32_e32 v58, 0x3d372713, v30
	v_mul_f32_e32 v58, v30, v58
	v_fma_f32 v58, v30, v58, v30
	v_mul_f32_e32 v58, 0xbfcc422a, v58
	v_mul_f32_e32 v58, 0x3fb8aa3b, v58
	v_exp_f32_e32 v58, v58
	v_mov_b32_e32 v169, v1
	v_add_f32_e32 v58, 1.0, v58
	v_rcp_f32_e32 v58, v58
	s_nop 0
	v_mul_f32_e32 v30, v30, v58
	v_mul_f32_e32 v58, 0x3d372713, v26
	v_mul_f32_e32 v58, v26, v58
	v_fma_f32 v58, v26, v58, v26
	v_mul_f32_e32 v58, 0xbfcc422a, v58
	v_mul_f32_e32 v58, 0x3fb8aa3b, v58
	v_exp_f32_e32 v58, v58
	s_nop 0
	v_add_f32_e32 v58, 1.0, v58
	v_rcp_f32_e32 v58, v58
	s_nop 0
	v_mul_f32_e32 v60, v26, v58
	v_mul_f32_e32 v26, 0x3d372713, v31
	v_mul_f32_e32 v26, v31, v26
	v_fma_f32 v26, v31, v26, v31
	v_mul_f32_e32 v26, 0xbfcc422a, v26
	v_mul_f32_e32 v26, 0x3fb8aa3b, v26
	v_exp_f32_e32 v26, v26
	v_lshl_add_u64 v[58:59], v[42:43], 0, v[168:169]
	v_add_f32_e32 v26, 1.0, v26
	v_rcp_f32_e32 v26, v26
	s_nop 0
	v_mul_f32_e32 v26, v31, v26
	v_mul_f32_e32 v31, 0x3d372713, v27
	v_mul_f32_e32 v31, v27, v31
	v_fma_f32 v31, v27, v31, v27
	v_mul_f32_e32 v31, 0xbfcc422a, v31
	v_mul_f32_e32 v31, 0x3fb8aa3b, v31
	v_exp_f32_e32 v31, v31
	v_cvt_pk_bf16_f32 v26, v30, v26
	s_nop 0
	v_add_f32_e32 v31, 1.0, v31
	v_rcp_f32_e32 v31, v31
	s_nop 0
	v_mul_f32_e32 v31, v27, v31
	v_mul_f32_e32 v27, 0x3d372713, v32
	v_mul_f32_e32 v27, v32, v27
	v_fma_f32 v27, v32, v27, v32
	v_mul_f32_e32 v27, 0xbfcc422a, v27
	v_mul_f32_e32 v27, 0x3fb8aa3b, v27
	v_exp_f32_e32 v27, v27
	s_nop 0
	v_add_f32_e32 v27, 1.0, v27
	v_rcp_f32_e32 v27, v27
	s_nop 0
	v_mul_f32_e32 v27, v32, v27
	v_mul_f32_e32 v32, 0x3d372713, v28
	v_mul_f32_e32 v32, v28, v32
	v_fma_f32 v32, v28, v32, v28
	v_mul_f32_e32 v32, 0xbfcc422a, v32
	v_mul_f32_e32 v32, 0x3fb8aa3b, v32
	v_exp_f32_e32 v32, v32
	s_nop 0
	v_add_f32_e32 v32, 1.0, v32
	v_rcp_f32_e32 v32, v32
	s_nop 0
	v_mul_f32_e32 v28, v28, v32
	v_mul_f32_e32 v32, 0x3d372713, v33
	v_mul_f32_e32 v32, v33, v32
	v_fma_f32 v32, v33, v32, v33
	v_mul_f32_e32 v32, 0xbfcc422a, v32
	v_mul_f32_e32 v32, 0x3fb8aa3b, v32
	v_exp_f32_e32 v32, v32
	s_nop 0
	v_add_f32_e32 v32, 1.0, v32
	v_rcp_f32_e32 v32, v32
	s_nop 0
	v_mul_f32_e32 v32, v33, v32
	v_mul_f32_e32 v33, 0x3d372713, v29
	v_mul_f32_e32 v33, v29, v33
	v_fma_f32 v33, v29, v33, v29
	v_mul_f32_e32 v33, 0xbfcc422a, v33
	v_mul_f32_e32 v33, 0x3fb8aa3b, v33
	v_exp_f32_e32 v33, v33
	v_cvt_pk_bf16_f32 v27, v27, v32
	v_mov_b64_e32 v[216:217], v[26:27]
	v_cvt_pk_bf16_f32 v60, v60, v31
	v_add_f32_e32 v33, 1.0, v33
	v_rcp_f32_e32 v33, v33
	s_nop 0
	v_mul_f32_e32 v29, v29, v33
	v_cvt_pk_bf16_f32 v61, v28, v29
	s_and_b64 vcc, exec, s[50:51]
	v_mov_b64_e32 v[218:219], v[60:61]
	s_nop 1
	v_permlane16_swap_b32_e32 v216, v218
	v_permlane16_swap_b32_e32 v217, v219
	v_lshl_add_u64 v[220:221], v[58:59], 0, v[222:223]
	global_store_dwordx4 v[220:221], v[216:219], off
	s_cbranch_vccnz .LBB0_449
	s_branch .LBB0_448

;     __device__ __forceinline__ void operator()(const f32x4 (&acc)[2][2][4][2], const Unit& u, int wr, int wc, int fr, int fq) const {
;     ...
;                     f32x4 v0 = acc[ai][bj][m][0], v1 = acc[ai][bj][m][1];
;                     const bool is_rope = (pn >= 2 && pn <= 6) || (pn == 9 && bj == 0);
;                     if (is_rope && lat) {
;                         const float cs[4] = {c01[0], c01[2], c23[0], c23[2]}, sn[4] = {c01[1], c01[3], c23[1], c23[3]};
; #pragma unroll
;                         for (int i = 0; i < 4; ++i) { const float x0 = v0[i], x1 = v1[i]; v0[i] = x0 * cs[i] - x1 * sn[i]; v1[i] = x1 * cs[i] + x0 * sn[i]; }
;                     }
.LBB0_467:
	v_mov_b64_e32 v[218:219], v[28:29]
	s_nop 1
	v_permlane16_swap_b32_e32 v216, v218
	v_permlane16_swap_b32_e32 v217, v219
	v_lshl_add_u64 v[220:221], v[26:27], 0, v[222:223]
	global_store_dwordx4 v[220:221], v[216:219], off
	s_and_b64 vcc, exec, s[46:47]
	s_cbranch_vccnz .LBB0_469
	s_waitcnt vmcnt(0) lgkmcnt(0)
	v_mul_f32_e32 v26, v12, v39
	v_mul_f32_e32 v28, v12, v38
	v_mov_b32_e32 v12, v17
	v_mov_b32_e32 v20, v35
	v_mov_b32_e32 v21, v37
	v_mul_f32_e32 v24, v16, v38
	v_mul_f32_e32 v30, v16, v39
	v_pk_mul_f32 v[32:33], v[12:13], v[40:41]
	v_mov_b32_e32 v16, v13
	v_mov_b32_e32 v18, v34
	v_mov_b32_e32 v19, v36
	v_pk_mul_f32 v[22:23], v[10:11], v[20:21]
	v_mov_b32_e32 v25, v32
	v_mov_b32_e32 v27, v33
	v_pk_mul_f32 v[12:13], v[16:17], v[40:41]
	v_pk_mul_f32 v[10:11], v[10:11], v[18:19]
	v_pk_fma_f32 v[18:19], v[14:15], v[18:19], v[22:23] neg_lo:[0,0,1] neg_hi:[0,0,1]
	v_pk_add_f32 v[22:23], v[24:25], v[26:27] neg_lo:[0,1] neg_hi:[0,1]
	v_mov_b32_e32 v31, v13
	v_mov_b32_e32 v29, v12
	v_pk_fma_f32 v[10:11], v[14:15], v[20:21], v[10:11]
	v_pk_add_f32 v[12:13], v[30:31], v[28:29]
	v_mov_b32_e32 v14, v18
	v_mov_b32_e32 v15, v19
	v_mov_b32_e32 v16, v22
	v_mov_b32_e32 v17, v23

;     __device__ __forceinline__ void operator()(const f32x4 (&acc)[2][2][4][2], const Unit& u, int wr, int wc, int fr, int fq) const {
;     ...
;                     if (pn <= 1) {
; #pragma unroll
;                         for (int i = 0; i < 4; ++i) { v0[i] = gelu_tanh_f(v0[i]); v1[i] = gelu_tanh_f(v1[i]); }
;                         bf16_t* p = UV + (size_t)r * 512 + pn * 256 + ctb;
;                         *(u32x2*)p = (u32x2){cvt_pk_bf16(v0[0], v0[1]), cvt_pk_bf16(v0[2], v0[3])}; *(u32x2*)(p + 16) = (u32x2){cvt_pk_bf16(v1[0], v1[1]), cvt_pk_bf16(v1[2], v1[3])};
;                     } else if (pn <= 4) {
;                         v0 = v0 * QSCALE; v1 = v1 * QSCALE;
;                         bf16_t* p = (pn <= 3) ? QB + (size_t)r * 512 + (pn - 2) * 256 + ctb : QC + (size_t)r * 256 + ctb;
;                         *(u32x2*)p = (u32x2){cvt_pk_bf16(v0[0], v0[1]), cvt_pk_bf16(v0[2], v0[3])}; *(u32x2*)(p + 16) = (u32x2){cvt_pk_bf16(v1[0], v1[1]), cvt_pk_bf16(v1[2], v1[3])};
;                     } else if (pn <= 6) {
;                         const int ck = (pn - 5) * 256 + ctb, head = ck >> 7, cw = ck & 127;
;                         bf16_t* p = KB + ((size_t)(b * 4 + head) * NKEY + keyidx) * 128 + cw;
;                         *(u32x2*)p = (u32x2){cvt_pk_bf16(v0[0], v0[1]), cvt_pk_bf16(v0[2], v0[3])}; *(u32x2*)(p + 16) = (u32x2){cvt_pk_bf16(v1[0], v1[1]), cvt_pk_bf16(v1[2], v1[3])};
;                     } else if (pn <= 8) {
;                         const int cv = (pn - 7) * 256 + ctb, head = cv >> 7, e = cv & 127;
;                         bf16_t* p = VBt + ((size_t)(b * 4 + head) * NKEY + keyidx) * 128 + e;
;                         *(u32x2*)p = (u32x2){cvt_pk_bf16(v0[0], v0[1]), cvt_pk_bf16(v0[2], v0[3])}; *(u32x2*)(p + 16) = (u32x2){cvt_pk_bf16(v1[0], v1[1]), cvt_pk_bf16(v1[2], v1[3])};
;                     } else {
;                         const int kv = wc >> 1, d = (wc & 1) * 32 + 4 * fq;
;                         if (bj == 0) {
;                             bf16_t* p = KC + ((size_t)(b * 2 + kv) * NKEY + keyidx) * 64 + d;
;                             *(u32x2*)p = (u32x2){cvt_pk_bf16(v0[0], v0[1]), cvt_pk_bf16(v0[2], v0[3])}; *(u32x2*)(p + 16) = (u32x2){cvt_pk_bf16(v1[0], v1[1]), cvt_pk_bf16(v1[2], v1[3])};
;                         } else {
;                             bf16_t* p = VCt + ((size_t)(b * 2 + kv) * NKEY + keyidx) * 64 + d;
.LBB0_483:
	s_and_b64 vcc, exec, s[50:51]
	v_mov_b64_e32 v[218:219], v[28:29]
	s_nop 1
	v_permlane16_swap_b32_e32 v216, v218
	v_permlane16_swap_b32_e32 v217, v219
	v_lshl_add_u64 v[220:221], v[26:27], 0, v[222:223]
	global_store_dwordx4 v[220:221], v[216:219], off
	s_cbranch_vccnz .LBB0_485

; __device__ __forceinline__ unsigned cvt_pk_bf16(float lo, float hi) { unsigned r; asm volatile("v_cvt_pk_bf16_f32 %0, %1, %2" : "=v"(r) : "v"(lo), "v"(hi)); return r; }
; __device__ __forceinline__ float gelu_tanh_f(float x) { const float y = 1.5957691216057308f * (x + 0.044715f * x * x * x); return x * __builtin_amdgcn_rcpf(1.f + __expf(-y)); }
;     __device__ __forceinline__ void operator()(const f32x4 (&acc)[2][2][4][2], const Unit& u, int wr, int wc, int fr, int fq) const {
;     ...
;                     if (pn <= 1) {
; #pragma unroll
;                         for (int i = 0; i < 4; ++i) { v0[i] = gelu_tanh_f(v0[i]); v1[i] = gelu_tanh_f(v1[i]); }
;                         bf16_t* p = UV + (size_t)r * 512 + pn * 256 + ctb;
;                         *(u32x2*)p = (u32x2){cvt_pk_bf16(v0[0], v0[1]), cvt_pk_bf16(v0[2], v0[3])}; *(u32x2*)(p + 16) = (u32x2){cvt_pk_bf16(v1[0], v1[1]), cvt_pk_bf16(v1[2], v1[3])};
.LBB0_500:
	v_mul_f32_e32 v26, 0x3d372713, v14
	v_mul_f32_e32 v26, v14, v26
	v_fma_f32 v26, v14, v26, v14
	v_mul_f32_e32 v26, 0xbfcc422a, v26
	v_mul_f32_e32 v26, 0x3fb8aa3b, v26
	v_exp_f32_e32 v26, v26
	v_mov_b32_e32 v169, v1
	v_add_f32_e32 v26, 1.0, v26
	v_rcp_f32_e32 v26, v26
	s_nop 0
	v_mul_f32_e32 v14, v14, v26
	v_mul_f32_e32 v26, 0x3d372713, v10
	v_mul_f32_e32 v26, v10, v26
	v_fma_f32 v26, v10, v26, v10
	v_mul_f32_e32 v26, 0xbfcc422a, v26
	v_mul_f32_e32 v26, 0x3fb8aa3b, v26
	v_exp_f32_e32 v26, v26
	s_nop 0
	v_add_f32_e32 v26, 1.0, v26
	v_rcp_f32_e32 v26, v26
	s_nop 0
	v_mul_f32_e32 v28, v10, v26
	v_mul_f32_e32 v10, 0x3d372713, v15
	v_mul_f32_e32 v10, v15, v10
	v_fma_f32 v10, v15, v10, v15
	v_mul_f32_e32 v10, 0xbfcc422a, v10
	v_mul_f32_e32 v10, 0x3fb8aa3b, v10
	v_exp_f32_e32 v10, v10
	v_lshl_add_u64 v[26:27], v[18:19], 0, v[168:169]
	v_add_f32_e32 v10, 1.0, v10
	v_rcp_f32_e32 v10, v10
	s_nop 0
	v_mul_f32_e32 v10, v15, v10
	v_mul_f32_e32 v15, 0x3d372713, v11
	v_mul_f32_e32 v15, v11, v15
	v_fma_f32 v15, v11, v15, v11
	v_mul_f32_e32 v15, 0xbfcc422a, v15
	v_mul_f32_e32 v15, 0x3fb8aa3b, v15
	v_exp_f32_e32 v15, v15
	v_cvt_pk_bf16_f32 v10, v14, v10
	s_nop 0
	v_add_f32_e32 v15, 1.0, v15
	v_rcp_f32_e32 v15, v15
	s_nop 0
	v_mul_f32_e32 v15, v11, v15
	v_mul_f32_e32 v11, 0x3d372713, v16
	v_mul_f32_e32 v11, v16, v11
	v_fma_f32 v11, v16, v11, v16
	v_mul_f32_e32 v11, 0xbfcc422a, v11
	v_mul_f32_e32 v11, 0x3fb8aa3b, v11
	v_exp_f32_e32 v11, v11
	s_nop 0
	v_add_f32_e32 v11, 1.0, v11
	v_rcp_f32_e32 v11, v11
	s_nop 0
	v_mul_f32_e32 v11, v16, v11
	v_mul_f32_e32 v16, 0x3d372713, v12
	v_mul_f32_e32 v16, v12, v16
	v_fma_f32 v16, v12, v16, v12
	v_mul_f32_e32 v16, 0xbfcc422a, v16
	v_mul_f32_e32 v16, 0x3fb8aa3b, v16
	v_exp_f32_e32 v16, v16
	s_nop 0
	v_add_f32_e32 v16, 1.0, v16
	v_rcp_f32_e32 v16, v16
	s_nop 0
	v_mul_f32_e32 v12, v12, v16
	v_mul_f32_e32 v16, 0x3d372713, v17
	v_mul_f32_e32 v16, v17, v16
	v_fma_f32 v16, v17, v16, v17
	v_mul_f32_e32 v16, 0xbfcc422a, v16
	v_mul_f32_e32 v16, 0x3fb8aa3b, v16
	v_exp_f32_e32 v16, v16
	s_nop 0
	v_add_f32_e32 v16, 1.0, v16
	v_rcp_f32_e32 v16, v16
	s_nop 0
	v_mul_f32_e32 v16, v17, v16
	v_mul_f32_e32 v17, 0x3d372713, v13
	v_mul_f32_e32 v17, v13, v17
	v_fma_f32 v17, v13, v17, v13
	v_mul_f32_e32 v17, 0xbfcc422a, v17
	v_mul_f32_e32 v17, 0x3fb8aa3b, v17
	v_exp_f32_e32 v17, v17
	v_cvt_pk_bf16_f32 v11, v11, v16
	v_mov_b64_e32 v[216:217], v[10:11]
	v_cvt_pk_bf16_f32 v28, v28, v15
	v_add_f32_e32 v17, 1.0, v17
	v_rcp_f32_e32 v17, v17
	s_nop 0
	v_mul_f32_e32 v13, v13, v17
	v_cvt_pk_bf16_f32 v29, v12, v13
	s_and_b64 vcc, exec, s[50:51]
	v_mov_b64_e32 v[218:219], v[28:29]
	s_nop 1
	v_permlane16_swap_b32_e32 v216, v218
	v_permlane16_swap_b32_e32 v217, v219
	v_lshl_add_u64 v[220:221], v[26:27], 0, v[222:223]
	global_store_dwordx4 v[220:221], v[216:219], off
	s_cbranch_vccnz .LBB0_485
	s_branch .LBB0_484

;     __device__ __forceinline__ void operator()(const f32x4 (&acc)[2][2][4][2], const Unit& u, int wr, int wc, int fr, int fq) const {
;     ...
;                     if (pn <= 1) {
; #pragma unroll
;                         for (int i = 0; i < 4; ++i) { v0[i] = gelu_tanh_f(v0[i]); v1[i] = gelu_tanh_f(v1[i]); }
;                         bf16_t* p = UV + (size_t)r * 512 + pn * 256 + ctb;
;                         *(u32x2*)p = (u32x2){cvt_pk_bf16(v0[0], v0[1]), cvt_pk_bf16(v0[2], v0[3])}; *(u32x2*)(p + 16) = (u32x2){cvt_pk_bf16(v1[0], v1[1]), cvt_pk_bf16(v1[2], v1[3])};
;                     } else if (pn <= 4) {
;                         v0 = v0 * QSCALE; v1 = v1 * QSCALE;
;                         bf16_t* p = (pn <= 3) ? QB + (size_t)r * 512 + (pn - 2) * 256 + ctb : QC + (size_t)r * 256 + ctb;
;                         *(u32x2*)p = (u32x2){cvt_pk_bf16(v0[0], v0[1]), cvt_pk_bf16(v0[2], v0[3])}; *(u32x2*)(p + 16) = (u32x2){cvt_pk_bf16(v1[0], v1[1]), cvt_pk_bf16(v1[2], v1[3])};
;                     } else if (pn <= 6) {
;                         const int ck = (pn - 5) * 256 + ctb, head = ck >> 7, cw = ck & 127;
;                         bf16_t* p = KB + ((size_t)(b * 4 + head) * NKEY + keyidx) * 128 + cw;
;                         *(u32x2*)p = (u32x2){cvt_pk_bf16(v0[0], v0[1]), cvt_pk_bf16(v0[2], v0[3])}; *(u32x2*)(p + 16) = (u32x2){cvt_pk_bf16(v1[0], v1[1]), cvt_pk_bf16(v1[2], v1[3])};
;                     } else if (pn <= 8) {
;                         const int cv = (pn - 7) * 256 + ctb, head = cv >> 7, e = cv & 127;
;                         bf16_t* p = VBt + ((size_t)(b * 4 + head) * NKEY + keyidx) * 128 + e;
;                         *(u32x2*)p = (u32x2){cvt_pk_bf16(v0[0], v0[1]), cvt_pk_bf16(v0[2], v0[3])}; *(u32x2*)(p + 16) = (u32x2){cvt_pk_bf16(v1[0], v1[1]), cvt_pk_bf16(v1[2], v1[3])};
;                     } else {
;                         const int kv = wc >> 1, d = (wc & 1) * 32 + 4 * fq;
;                         if (bj == 0) {
;                             bf16_t* p = KC + ((size_t)(b * 2 + kv) * NKEY + keyidx) * 64 + d;
;                             *(u32x2*)p = (u32x2){cvt_pk_bf16(v0[0], v0[1]), cvt_pk_bf16(v0[2], v0[3])}; *(u32x2*)(p + 16) = (u32x2){cvt_pk_bf16(v1[0], v1[1]), cvt_pk_bf16(v1[2], v1[3])};
;                         } else {
;                             bf16_t* p = VCt + ((size_t)(b * 2 + kv) * NKEY + keyidx) * 64 + d;
.LBB0_503:
	v_mov_b64_e32 v[218:219], v[12:13]
	s_nop 1
	v_permlane16_swap_b32_e32 v216, v218
	v_permlane16_swap_b32_e32 v217, v219
	v_lshl_add_u64 v[220:221], v[10:11], 0, v[222:223]
	global_store_dwordx4 v[220:221], v[216:219], off
	v_readlane_b32 s60, v254, 41
	s_andn2_b64 vcc, exec, s[40:41]
	s_mov_b64 s[12:13], -1
	v_readlane_b32 s61, v254, 42
	s_cbranch_vccnz .LBB0_190
	v_readlane_b32 s12, v255, 8
	v_readlane_b32 s13, v255, 9
	s_andn2_b64 vcc, exec, s[12:13]
	s_cbranch_vccnz .LBB0_189
	s_barrier
	s_branch .LBB0_189
